# G + modulate row loops (k0,k3,k11): no store-ack wait at loop top, param reload path self-waits
# speedup vs baseline: 1.0005x; 1.0005x over previous
; #define GAS __attribute__((address_space(1)))
; __device__ __forceinline__ unsigned pk2(float lo, float hi) { return f2bf(lo) | (f2bf(hi) << 16); }
; __device__ __forceinline__ void modulate_phase(Frame& F, const float* x, bf16* H, const float* gnorm, const float* modsub) {
;     ...
;         float s = 0.f;
; #pragma unroll
;         for (int j = 0; j < 8; ++j) s += (v[j].x * v[j].x + v[j].y * v[j].y) + (v[j].z * v[j].z + v[j].w * v[j].w);
;         const float rstd = 1.0f / sqrtf(wave_sum(s) * (1.0f / D) + RMS_EPS);
;         GAS unsigned long long* o8 = (GAS unsigned long long*)(H + (size_t)r * D) + F.lane;
; #pragma unroll
;         for (int j = 0; j < 8; ++j) { const f32x4 y = v[j] * rstd * gs[j] + sh[j];
;             o8[64 * j] = (unsigned long long)pk2(y.x, y.y) | ((unsigned long long)pk2(y.z, y.w) << 32); }
.LBB0_216:
	s_nop 0
	v_mul_f32_e32 v0, v95, v95
	v_mul_f32_e32 v149, v97, v97
	v_fmac_f32_e32 v0, v94, v94
	v_fmac_f32_e32 v149, v96, v96
	v_add_f32_e32 v0, v0, v149
	v_mul_f32_e32 v149, v91, v91
	v_mul_f32_e32 v150, v93, v93
	v_fmac_f32_e32 v149, v90, v90
	v_fmac_f32_e32 v150, v92, v92
	v_add_f32_e32 v149, v149, v150
	v_add_f32_e32 v0, v0, v149
	v_mul_f32_e32 v149, v55, v55
	v_mul_f32_e32 v150, v57, v57
	v_fmac_f32_e32 v149, v54, v54
	v_fmac_f32_e32 v150, v56, v56
	v_add_f32_e32 v149, v149, v150
	v_add_f32_e32 v0, v149, v0
	v_mul_f32_e32 v149, v43, v43
	v_mul_f32_e32 v150, v45, v45
	v_fmac_f32_e32 v149, v42, v42
	v_fmac_f32_e32 v150, v44, v44
	v_add_f32_e32 v149, v149, v150
	v_add_f32_e32 v0, v149, v0
	v_mul_f32_e32 v149, v31, v31
	v_mul_f32_e32 v150, v33, v33
	v_fmac_f32_e32 v149, v30, v30
	v_fmac_f32_e32 v150, v32, v32
	v_add_f32_e32 v149, v149, v150
	v_add_f32_e32 v0, v149, v0
	v_mul_f32_e32 v149, v27, v27
	v_mul_f32_e32 v150, v29, v29
	v_fmac_f32_e32 v149, v26, v26
	v_fmac_f32_e32 v150, v28, v28
	v_add_f32_e32 v149, v149, v150
	v_add_f32_e32 v0, v149, v0
	v_mul_f32_e32 v149, v15, v15
	v_mul_f32_e32 v150, v17, v17
	v_fmac_f32_e32 v149, v14, v14
	v_fmac_f32_e32 v150, v16, v16
	v_add_f32_e32 v149, v149, v150
	v_add_f32_e32 v0, v149, v0
	v_mul_f32_e32 v149, v11, v11
	v_mul_f32_e32 v150, v13, v13
	v_fmac_f32_e32 v149, v10, v10
	v_fmac_f32_e32 v150, v12, v12
	v_add_f32_e32 v149, v149, v150
	v_add_f32_e32 v0, v149, v0
	ds_swizzle_b32 v149, v0 offset:swizzle(SWAP,1)
	s_waitcnt lgkmcnt(0)
	v_add_f32_e32 v0, v0, v149
	ds_swizzle_b32 v149, v0 offset:swizzle(SWAP,2)
	s_waitcnt lgkmcnt(0)
	v_add_f32_e32 v0, v0, v149
	ds_swizzle_b32 v149, v0 offset:swizzle(SWAP,4)
	s_waitcnt lgkmcnt(0)
	v_add_f32_e32 v0, v0, v149
	ds_swizzle_b32 v149, v0 offset:swizzle(SWAP,8)
	s_waitcnt lgkmcnt(0)
	v_add_f32_e32 v0, v0, v149
	ds_swizzle_b32 v149, v0 offset:swizzle(SWAP,16)
	s_waitcnt lgkmcnt(0)
	v_add_f32_e32 v0, v0, v149
	v_mov_b32_e32 v149, v0
	s_nop 1
	v_permlane32_swap_b32_e32 v0, v149
	v_add_f32_e32 v0, v0, v149
	v_fmamk_f32 v0, v0, 0x3a000000, v202
	v_mul_f32_e32 v149, 0x4f800000, v0
	v_cmp_gt_f32_e32 vcc, s60, v0
	s_nop 1
	v_cndmask_b32_e32 v0, v0, v149, vcc
	v_sqrt_f32_e32 v149, v0
	s_nop 0
	v_add_u32_e32 v150, -1, v149
	v_fma_f32 v151, -v150, v149, v0
	v_cmp_ge_f32_e64 s[36:37], 0, v151
	v_add_u32_e32 v151, 1, v149
	s_nop 0
	v_cndmask_b32_e64 v150, v149, v150, s[36:37]
	v_fma_f32 v149, -v151, v149, v0
	v_cmp_lt_f32_e64 s[36:37], 0, v149
	s_nop 1
	v_cndmask_b32_e64 v149, v150, v151, s[36:37]
	v_mul_f32_e32 v150, 0x37800000, v149
	v_cndmask_b32_e32 v149, v149, v150, vcc
	v_cmp_class_f32_e32 vcc, v0, v203
	s_nop 1
	v_cndmask_b32_e32 v0, v149, v0, vcc
	v_div_scale_f32 v149, s[12:13], v0, v0, 1.0
	v_rcp_f32_e32 v150, v149
	s_nop 0
	v_fma_f32 v151, -v149, v150, 1.0
	v_fmac_f32_e32 v150, v151, v150
	v_div_scale_f32 v151, vcc, 1.0, v0, 1.0
	v_mul_f32_e32 v152, v151, v150
	v_fma_f32 v153, -v149, v152, v151
	v_fmac_f32_e32 v152, v153, v150
	v_fma_f32 v149, -v149, v152, v151
	v_div_fmas_f32 v149, v149, v150, v152
	v_div_fixup_f32 v0, v149, v0, 1.0
	v_pk_mul_f32 v[94:95], v[94:95], v[0:1] op_sel_hi:[1,0]
	v_pk_mul_f32 v[96:97], v[96:97], v[0:1] op_sel_hi:[1,0]
	v_pk_fma_f32 v[94:95], v[2:3], v[94:95], v[6:7]
	v_pk_fma_f32 v[96:97], v[4:5], v[96:97], v[8:9]
	v_bfe_u32 v150, v94, 16, 1
	v_add3_u32 v94, v94, v150, s94
	v_bfe_u32 v150, v95, 16, 1
	v_lshrrev_b32_e32 v94, 16, v94
	v_add3_u32 v95, v95, v150, s94
	v_and_or_b32 v94, v95, s95, v94
	v_bfe_u32 v95, v96, 16, 1
	v_add3_u32 v95, v96, v95, s94
	v_bfe_u32 v96, v97, 16, 1
	v_lshrrev_b32_e32 v95, 16, v95
	v_add3_u32 v96, v97, v96, s94
	v_pk_mul_f32 v[90:91], v[90:91], v[0:1] op_sel_hi:[1,0]
	v_lshlrev_b32_e32 v149, 3, v130
	v_and_or_b32 v95, v96, s95, v95
	v_pk_fma_f32 v[90:91], v[22:23], v[90:91], v[18:19]
	global_store_dwordx2 v149, v[94:95], s[8:9]
	v_bfe_u32 v94, v90, 16, 1
	v_pk_mul_f32 v[92:93], v[92:93], v[0:1] op_sel_hi:[1,0]
	v_add3_u32 v90, v90, v94, s94
	v_bfe_u32 v94, v91, 16, 1
	v_pk_fma_f32 v[92:93], v[24:25], v[92:93], v[20:21]
	v_lshrrev_b32_e32 v90, 16, v90
	v_add3_u32 v91, v91, v94, s94
	v_and_or_b32 v90, v91, s95, v90
	v_bfe_u32 v91, v92, 16, 1
	v_add3_u32 v91, v92, v91, s94
	v_bfe_u32 v92, v93, 16, 1
	v_lshrrev_b32_e32 v91, 16, v91
	v_add3_u32 v92, v93, v92, s94
	v_pk_mul_f32 v[54:55], v[54:55], v[0:1] op_sel_hi:[1,0]
	v_and_or_b32 v91, v92, s95, v91
	v_pk_fma_f32 v[54:55], v[38:39], v[54:55], v[34:35]
	global_store_dwordx2 v149, v[90:91], s[8:9] offset:512
	v_bfe_u32 v90, v54, 16, 1
	v_pk_mul_f32 v[56:57], v[56:57], v[0:1] op_sel_hi:[1,0]
; #define GAS __attribute__((address_space(1)))
; __device__ __forceinline__ unsigned pk2(float lo, float hi) { return f2bf(lo) | (f2bf(hi) << 16); }
; __device__ __forceinline__ void modulate_phase(Frame& F, const float* x, bf16* H, const float* gnorm, const float* modsub) {
;     ...
;         GAS unsigned long long* o8 = (GAS unsigned long long*)(H + (size_t)r * D) + F.lane;
; #pragma unroll
;         for (int j = 0; j < 8; ++j) { const f32x4 y = v[j] * rstd * gs[j] + sh[j];
;             o8[64 * j] = (unsigned long long)pk2(y.x, y.y) | ((unsigned long long)pk2(y.z, y.w) << 32); }
; #pragma unroll
;         for (int j = 0; j < 8; ++j) v[j] = nv[j];
	v_add3_u32 v54, v54, v90, s94
	v_bfe_u32 v90, v55, 16, 1
	v_pk_fma_f32 v[56:57], v[40:41], v[56:57], v[36:37]
	v_lshrrev_b32_e32 v54, 16, v54
	v_add3_u32 v55, v55, v90, s94
	v_and_or_b32 v54, v55, s95, v54
	v_bfe_u32 v55, v56, 16, 1
	v_add3_u32 v55, v56, v55, s94
	v_bfe_u32 v56, v57, 16, 1
	v_lshrrev_b32_e32 v55, 16, v55
	v_add3_u32 v56, v57, v56, s94
	v_pk_mul_f32 v[42:43], v[42:43], v[0:1] op_sel_hi:[1,0]
	v_and_or_b32 v55, v56, s95, v55
	v_pk_fma_f32 v[42:43], v[86:87], v[42:43], v[78:79]
	global_store_dwordx2 v149, v[54:55], s[8:9] offset:1024
	v_bfe_u32 v54, v42, 16, 1
	v_pk_mul_f32 v[44:45], v[44:45], v[0:1] op_sel_hi:[1,0]
	v_add3_u32 v42, v42, v54, s94
	v_bfe_u32 v54, v43, 16, 1
	v_pk_fma_f32 v[44:45], v[88:89], v[44:45], v[80:81]
	v_lshrrev_b32_e32 v42, 16, v42
	v_add3_u32 v43, v43, v54, s94
	v_and_or_b32 v42, v43, s95, v42
	v_bfe_u32 v43, v44, 16, 1
	v_add3_u32 v43, v44, v43, s94
	v_bfe_u32 v44, v45, 16, 1
	v_lshrrev_b32_e32 v43, 16, v43
	v_add3_u32 v44, v45, v44, s94
	v_pk_mul_f32 v[30:31], v[30:31], v[0:1] op_sel_hi:[1,0]
	v_and_or_b32 v43, v44, s95, v43
	v_pk_fma_f32 v[30:31], v[102:103], v[30:31], v[98:99]
	global_store_dwordx2 v149, v[42:43], s[8:9] offset:1536
	v_bfe_u32 v42, v30, 16, 1
	v_pk_mul_f32 v[32:33], v[32:33], v[0:1] op_sel_hi:[1,0]
	v_add3_u32 v30, v30, v42, s94
	v_bfe_u32 v42, v31, 16, 1
	v_pk_fma_f32 v[32:33], v[104:105], v[32:33], v[100:101]
	v_lshrrev_b32_e32 v30, 16, v30
	v_add3_u32 v31, v31, v42, s94
	v_and_or_b32 v30, v31, s95, v30
	v_bfe_u32 v31, v32, 16, 1
	v_add3_u32 v31, v32, v31, s94
	v_bfe_u32 v32, v33, 16, 1
	v_lshrrev_b32_e32 v31, 16, v31
	v_add3_u32 v32, v33, v32, s94
	v_pk_mul_f32 v[26:27], v[26:27], v[0:1] op_sel_hi:[1,0]
	v_and_or_b32 v31, v32, s95, v31
	v_pk_fma_f32 v[26:27], v[110:111], v[26:27], v[106:107]
	global_store_dwordx2 v149, v[30:31], s[8:9] offset:2048
	v_bfe_u32 v30, v26, 16, 1
	v_pk_mul_f32 v[28:29], v[28:29], v[0:1] op_sel_hi:[1,0]
	v_add3_u32 v26, v26, v30, s94
	v_bfe_u32 v30, v27, 16, 1
	v_pk_fma_f32 v[28:29], v[112:113], v[28:29], v[108:109]
	v_lshrrev_b32_e32 v26, 16, v26
	v_add3_u32 v27, v27, v30, s94
	v_and_or_b32 v26, v27, s95, v26
	v_bfe_u32 v27, v28, 16, 1
	v_add3_u32 v27, v28, v27, s94
	v_bfe_u32 v28, v29, 16, 1
	v_lshrrev_b32_e32 v27, 16, v27
	v_add3_u32 v28, v29, v28, s94
	v_pk_mul_f32 v[14:15], v[14:15], v[0:1] op_sel_hi:[1,0]
	v_pk_mul_f32 v[10:11], v[10:11], v[0:1] op_sel_hi:[1,0]
	v_and_or_b32 v27, v28, s95, v27
	v_pk_fma_f32 v[14:15], v[118:119], v[14:15], v[114:115]
	v_pk_fma_f32 v[10:11], v[122:123], v[10:11], v[126:127]
	global_store_dwordx2 v149, v[26:27], s[8:9] offset:2560
	v_pk_mul_f32 v[16:17], v[16:17], v[0:1] op_sel_hi:[1,0]
	v_bfe_u32 v26, v14, 16, 1
	v_pk_mul_f32 v[12:13], v[12:13], v[0:1] op_sel_hi:[1,0]
	v_bfe_u32 v0, v10, 16, 1
	v_add3_u32 v14, v14, v26, s94
	v_bfe_u32 v26, v15, 16, 1
	v_add3_u32 v0, v10, v0, s94
	v_bfe_u32 v10, v11, 16, 1
	v_pk_fma_f32 v[16:17], v[120:121], v[16:17], v[116:117]
	v_lshrrev_b32_e32 v14, 16, v14
	v_add3_u32 v15, v15, v26, s94
	v_pk_fma_f32 v[12:13], v[124:125], v[12:13], v[128:129]
	v_lshrrev_b32_e32 v0, 16, v0
	v_add3_u32 v10, v11, v10, s94
	v_and_or_b32 v14, v15, s95, v14
	v_bfe_u32 v15, v16, 16, 1
	v_and_or_b32 v10, v10, s95, v0
	v_bfe_u32 v0, v12, 16, 1
	v_add3_u32 v15, v16, v15, s94
	v_bfe_u32 v16, v17, 16, 1
	v_add3_u32 v0, v12, v0, s94
	v_bfe_u32 v11, v13, 16, 1
	v_lshrrev_b32_e32 v15, 16, v15
	v_add3_u32 v16, v17, v16, s94
	v_lshrrev_b32_e32 v0, 16, v0
	v_add3_u32 v11, v13, v11, s94
	v_and_or_b32 v15, v16, s95, v15
	v_and_or_b32 v11, v11, s95, v0
	global_store_dwordx2 v149, v[14:15], s[8:9] offset:3072
	global_store_dwordx2 v149, v[10:11], s[8:9] offset:3584
	s_add_u32 s8, s8, 0x1000
	s_addc_u32 s9, s9, 0
	s_cmp_lt_i32 s6, s2
	s_waitcnt vmcnt(8)
	v_mov_b32_e32 v94, v82
	v_mov_b32_e32 v95, v83
	v_mov_b32_e32 v96, v84
	v_mov_b32_e32 v97, v85
	v_mov_b32_e32 v90, v74
	v_mov_b32_e32 v91, v75
	v_mov_b32_e32 v92, v76
	v_mov_b32_e32 v93, v77
	v_mov_b32_e32 v54, v66
	v_mov_b32_e32 v55, v67
	v_mov_b32_e32 v56, v68
	v_mov_b32_e32 v57, v69
	v_mov_b32_e32 v42, v58
	v_mov_b32_e32 v43, v59
	v_mov_b32_e32 v44, v60
	v_mov_b32_e32 v45, v61
	v_mov_b32_e32 v30, v70
	v_mov_b32_e32 v31, v71
	v_mov_b32_e32 v32, v72
	v_mov_b32_e32 v33, v73
	v_mov_b32_e32 v26, v62
	v_mov_b32_e32 v27, v63
	v_mov_b32_e32 v28, v64
	v_mov_b32_e32 v29, v65
	v_mov_b32_e32 v14, v50
	v_mov_b32_e32 v15, v51
	v_mov_b32_e32 v16, v52
	v_mov_b32_e32 v17, v53
	v_mov_b32_e32 v10, v46
	v_mov_b32_e32 v11, v47
	v_mov_b32_e32 v12, v48
	v_mov_b32_e32 v13, v49
	s_cbranch_scc0 .LBB0_219

; #define GAS __attribute__((address_space(1)))
; __device__ __forceinline__ unsigned pk2(float lo, float hi) { return f2bf(lo) | (f2bf(hi) << 16); }
; __device__ __forceinline__ void modulate_phase(Frame& F, const float* x, bf16* H, const float* gnorm, const float* modsub) {
;     ...
;         float s = 0.f;
; #pragma unroll
;         for (int j = 0; j < 8; ++j) s += (v[j].x * v[j].x + v[j].y * v[j].y) + (v[j].z * v[j].z + v[j].w * v[j].w);
;         const float rstd = 1.0f / sqrtf(wave_sum(s) * (1.0f / D) + RMS_EPS);
;         GAS unsigned long long* o8 = (GAS unsigned long long*)(H + (size_t)r * D) + F.lane;
; #pragma unroll
;         for (int j = 0; j < 8; ++j) { const f32x4 y = v[j] * rstd * gs[j] + sh[j];
;             o8[64 * j] = (unsigned long long)pk2(y.x, y.y) | ((unsigned long long)pk2(y.z, y.w) << 32); }
.LBB0_418:
	s_nop 0
	v_mul_f32_e32 v0, v95, v95
	v_mul_f32_e32 v155, v97, v97
	v_fmac_f32_e32 v0, v94, v94
	v_fmac_f32_e32 v155, v96, v96
	v_add_f32_e32 v0, v0, v155
	v_mul_f32_e32 v155, v83, v83
	v_mul_f32_e32 v156, v85, v85
	v_fmac_f32_e32 v155, v82, v82
	v_fmac_f32_e32 v156, v84, v84
	v_add_f32_e32 v155, v155, v156
	v_add_f32_e32 v0, v0, v155
	v_mul_f32_e32 v155, v47, v47
	v_mul_f32_e32 v156, v49, v49
	v_fmac_f32_e32 v155, v46, v46
	v_fmac_f32_e32 v156, v48, v48
	v_add_f32_e32 v155, v155, v156
	v_add_f32_e32 v0, v155, v0
	v_mul_f32_e32 v155, v35, v35
	v_mul_f32_e32 v156, v37, v37
	v_fmac_f32_e32 v155, v34, v34
	v_fmac_f32_e32 v156, v36, v36
	v_add_f32_e32 v155, v155, v156
	v_add_f32_e32 v0, v155, v0
	v_mul_f32_e32 v155, v31, v31
	v_mul_f32_e32 v156, v33, v33
	v_fmac_f32_e32 v155, v30, v30
	v_fmac_f32_e32 v156, v32, v32
	v_add_f32_e32 v155, v155, v156
	v_add_f32_e32 v0, v155, v0
	v_mul_f32_e32 v155, v19, v19
	v_mul_f32_e32 v156, v21, v21
	v_fmac_f32_e32 v155, v18, v18
	v_fmac_f32_e32 v156, v20, v20
	v_add_f32_e32 v155, v155, v156
	v_add_f32_e32 v0, v155, v0
	v_mul_f32_e32 v155, v15, v15
	v_mul_f32_e32 v156, v17, v17
	v_fmac_f32_e32 v155, v14, v14
	v_fmac_f32_e32 v156, v16, v16
	v_add_f32_e32 v155, v155, v156
	v_add_f32_e32 v0, v155, v0
	v_mul_f32_e32 v155, v3, v3
	v_mul_f32_e32 v156, v5, v5
	v_fmac_f32_e32 v155, v2, v2
	v_fmac_f32_e32 v156, v4, v4
	v_add_f32_e32 v155, v155, v156
	v_add_f32_e32 v0, v155, v0
	ds_swizzle_b32 v155, v0 offset:swizzle(SWAP,1)
	s_waitcnt lgkmcnt(0)
	v_add_f32_e32 v0, v0, v155
	ds_swizzle_b32 v155, v0 offset:swizzle(SWAP,2)
	s_waitcnt lgkmcnt(0)
	v_add_f32_e32 v0, v0, v155
	ds_swizzle_b32 v155, v0 offset:swizzle(SWAP,4)
	s_waitcnt lgkmcnt(0)
	v_add_f32_e32 v0, v0, v155
	ds_swizzle_b32 v155, v0 offset:swizzle(SWAP,8)
	s_waitcnt lgkmcnt(0)
	v_add_f32_e32 v0, v0, v155
	ds_swizzle_b32 v155, v0 offset:swizzle(SWAP,16)
	s_waitcnt lgkmcnt(0)
	v_add_f32_e32 v0, v0, v155
	v_mov_b32_e32 v155, v0
	s_nop 1
	v_permlane32_swap_b32_e32 v0, v155
	v_add_f32_e32 v0, v0, v155
	v_fmamk_f32 v0, v0, 0x3a000000, v202
	v_mul_f32_e32 v155, 0x4f800000, v0
	v_cmp_gt_f32_e32 vcc, s60, v0
	s_nop 1
	v_cndmask_b32_e32 v0, v0, v155, vcc
	v_sqrt_f32_e32 v155, v0
	s_nop 0
	v_add_u32_e32 v156, -1, v155
	v_fma_f32 v157, -v156, v155, v0
	v_cmp_ge_f32_e64 s[38:39], 0, v157
	v_add_u32_e32 v157, 1, v155
	s_nop 0
	v_cndmask_b32_e64 v156, v155, v156, s[38:39]
	v_fma_f32 v155, -v157, v155, v0
	v_cmp_lt_f32_e64 s[38:39], 0, v155
	s_nop 1
	v_cndmask_b32_e64 v155, v156, v157, s[38:39]
	v_mul_f32_e32 v156, 0x37800000, v155
	v_cndmask_b32_e32 v155, v155, v156, vcc
	v_cmp_class_f32_e32 vcc, v0, v203
	s_nop 1
	v_cndmask_b32_e32 v0, v155, v0, vcc
	v_div_scale_f32 v155, s[10:11], v0, v0, 1.0
	v_rcp_f32_e32 v156, v155
	s_nop 0
	v_fma_f32 v157, -v155, v156, 1.0
	v_fmac_f32_e32 v156, v157, v156
	v_div_scale_f32 v157, vcc, 1.0, v0, 1.0
	v_mul_f32_e32 v158, v157, v156
	v_fma_f32 v159, -v155, v158, v157
	v_fmac_f32_e32 v158, v159, v156
	v_fma_f32 v155, -v155, v158, v157
	v_div_fmas_f32 v155, v155, v156, v158
	v_div_fixup_f32 v0, v155, v0, 1.0
	v_pk_mul_f32 v[94:95], v[94:95], v[0:1] op_sel_hi:[1,0]
	v_pk_mul_f32 v[96:97], v[96:97], v[0:1] op_sel_hi:[1,0]
	v_pk_fma_f32 v[94:95], v[6:7], v[94:95], v[10:11]
	v_pk_fma_f32 v[96:97], v[8:9], v[96:97], v[12:13]
	v_bfe_u32 v156, v94, 16, 1
	v_add3_u32 v94, v94, v156, s94
	v_bfe_u32 v156, v95, 16, 1
	v_lshrrev_b32_e32 v94, 16, v94
	v_add3_u32 v95, v95, v156, s94
	v_and_or_b32 v94, v95, s95, v94
	v_bfe_u32 v95, v96, 16, 1
	v_add3_u32 v95, v96, v95, s94
	v_bfe_u32 v96, v97, 16, 1
	v_lshrrev_b32_e32 v95, 16, v95
	v_add3_u32 v96, v97, v96, s94
	v_pk_mul_f32 v[82:83], v[82:83], v[0:1] op_sel_hi:[1,0]
	v_lshlrev_b32_e32 v155, 3, v130
	v_and_or_b32 v95, v96, s95, v95
	v_pk_fma_f32 v[82:83], v[26:27], v[82:83], v[22:23]
	global_store_dwordx2 v155, v[94:95], s[6:7]
	v_bfe_u32 v94, v82, 16, 1
	v_pk_mul_f32 v[84:85], v[84:85], v[0:1] op_sel_hi:[1,0]
	v_add3_u32 v82, v82, v94, s94
	v_bfe_u32 v94, v83, 16, 1
	v_pk_fma_f32 v[84:85], v[28:29], v[84:85], v[24:25]
	v_lshrrev_b32_e32 v82, 16, v82
	v_add3_u32 v83, v83, v94, s94
	v_and_or_b32 v82, v83, s95, v82
	v_bfe_u32 v83, v84, 16, 1
	v_add3_u32 v83, v84, v83, s94
	v_bfe_u32 v84, v85, 16, 1
	v_lshrrev_b32_e32 v83, 16, v83
	v_add3_u32 v84, v85, v84, s94
	v_pk_mul_f32 v[46:47], v[46:47], v[0:1] op_sel_hi:[1,0]
	v_and_or_b32 v83, v84, s95, v83
	v_pk_fma_f32 v[46:47], v[42:43], v[46:47], v[38:39]
	global_store_dwordx2 v155, v[82:83], s[6:7] offset:512
	v_bfe_u32 v82, v46, 16, 1
; #define GAS __attribute__((address_space(1)))
; __device__ __forceinline__ unsigned pk2(float lo, float hi) { return f2bf(lo) | (f2bf(hi) << 16); }
; __device__ __forceinline__ void modulate_phase(Frame& F, const float* x, bf16* H, const float* gnorm, const float* modsub) {
;     ...
;         GAS unsigned long long* o8 = (GAS unsigned long long*)(H + (size_t)r * D) + F.lane;
; #pragma unroll
;         for (int j = 0; j < 8; ++j) { const f32x4 y = v[j] * rstd * gs[j] + sh[j];
;             o8[64 * j] = (unsigned long long)pk2(y.x, y.y) | ((unsigned long long)pk2(y.z, y.w) << 32); }
; #pragma unroll
;         for (int j = 0; j < 8; ++j) v[j] = nv[j];
	v_pk_mul_f32 v[48:49], v[48:49], v[0:1] op_sel_hi:[1,0]
	v_add3_u32 v46, v46, v82, s94
	v_bfe_u32 v82, v47, 16, 1
	v_pk_fma_f32 v[48:49], v[44:45], v[48:49], v[40:41]
	v_lshrrev_b32_e32 v46, 16, v46
	v_add3_u32 v47, v47, v82, s94
	v_and_or_b32 v46, v47, s95, v46
	v_bfe_u32 v47, v48, 16, 1
	v_add3_u32 v47, v48, v47, s94
	v_bfe_u32 v48, v49, 16, 1
	v_lshrrev_b32_e32 v47, 16, v47
	v_add3_u32 v48, v49, v48, s94
	v_pk_mul_f32 v[34:35], v[34:35], v[0:1] op_sel_hi:[1,0]
	v_and_or_b32 v47, v48, s95, v47
	v_pk_fma_f32 v[34:35], v[90:91], v[34:35], v[78:79]
	global_store_dwordx2 v155, v[46:47], s[6:7] offset:1024
	v_bfe_u32 v46, v34, 16, 1
	v_pk_mul_f32 v[36:37], v[36:37], v[0:1] op_sel_hi:[1,0]
	v_add3_u32 v34, v34, v46, s94
	v_bfe_u32 v46, v35, 16, 1
	v_pk_fma_f32 v[36:37], v[92:93], v[36:37], v[80:81]
	v_lshrrev_b32_e32 v34, 16, v34
	v_add3_u32 v35, v35, v46, s94
	v_and_or_b32 v34, v35, s95, v34
	v_bfe_u32 v35, v36, 16, 1
	v_add3_u32 v35, v36, v35, s94
	v_bfe_u32 v36, v37, 16, 1
	v_lshrrev_b32_e32 v35, 16, v35
	v_add3_u32 v36, v37, v36, s94
	v_pk_mul_f32 v[30:31], v[30:31], v[0:1] op_sel_hi:[1,0]
	v_and_or_b32 v35, v36, s95, v35
	v_pk_fma_f32 v[30:31], v[102:103], v[30:31], v[98:99]
	global_store_dwordx2 v155, v[34:35], s[6:7] offset:1536
	v_bfe_u32 v34, v30, 16, 1
	v_pk_mul_f32 v[32:33], v[32:33], v[0:1] op_sel_hi:[1,0]
	v_add3_u32 v30, v30, v34, s94
	v_bfe_u32 v34, v31, 16, 1
	v_pk_fma_f32 v[32:33], v[104:105], v[32:33], v[100:101]
	v_lshrrev_b32_e32 v30, 16, v30
	v_add3_u32 v31, v31, v34, s94
	v_and_or_b32 v30, v31, s95, v30
	v_bfe_u32 v31, v32, 16, 1
	v_add3_u32 v31, v32, v31, s94
	v_bfe_u32 v32, v33, 16, 1
	v_lshrrev_b32_e32 v31, 16, v31
	v_add3_u32 v32, v33, v32, s94
	v_pk_mul_f32 v[18:19], v[18:19], v[0:1] op_sel_hi:[1,0]
	v_and_or_b32 v31, v32, s95, v31
	v_pk_fma_f32 v[18:19], v[110:111], v[18:19], v[106:107]
	global_store_dwordx2 v155, v[30:31], s[6:7] offset:2048
	v_bfe_u32 v30, v18, 16, 1
	v_pk_mul_f32 v[20:21], v[20:21], v[0:1] op_sel_hi:[1,0]
	v_add3_u32 v18, v18, v30, s94
	v_bfe_u32 v30, v19, 16, 1
	v_pk_fma_f32 v[20:21], v[112:113], v[20:21], v[108:109]
	v_lshrrev_b32_e32 v18, 16, v18
	v_add3_u32 v19, v19, v30, s94
	v_and_or_b32 v18, v19, s95, v18
	v_bfe_u32 v19, v20, 16, 1
	v_add3_u32 v19, v20, v19, s94
	v_bfe_u32 v20, v21, 16, 1
	v_lshrrev_b32_e32 v19, 16, v19
	v_add3_u32 v20, v21, v20, s94
	v_pk_mul_f32 v[14:15], v[14:15], v[0:1] op_sel_hi:[1,0]
	v_pk_mul_f32 v[2:3], v[2:3], v[0:1] op_sel_hi:[1,0]
	v_and_or_b32 v19, v20, s95, v19
	v_pk_fma_f32 v[14:15], v[118:119], v[14:15], v[114:115]
	v_pk_fma_f32 v[2:3], v[122:123], v[2:3], v[126:127]
	global_store_dwordx2 v155, v[18:19], s[6:7] offset:2560
	v_pk_mul_f32 v[16:17], v[16:17], v[0:1] op_sel_hi:[1,0]
	v_bfe_u32 v18, v14, 16, 1
	v_pk_mul_f32 v[4:5], v[4:5], v[0:1] op_sel_hi:[1,0]
	v_bfe_u32 v0, v2, 16, 1
	v_add3_u32 v14, v14, v18, s94
	v_bfe_u32 v18, v15, 16, 1
	v_add3_u32 v0, v2, v0, s94
	v_bfe_u32 v2, v3, 16, 1
	v_pk_fma_f32 v[16:17], v[120:121], v[16:17], v[116:117]
	v_lshrrev_b32_e32 v14, 16, v14
	v_add3_u32 v15, v15, v18, s94
	v_pk_fma_f32 v[4:5], v[124:125], v[4:5], v[128:129]
	v_lshrrev_b32_e32 v0, 16, v0
	v_add3_u32 v2, v3, v2, s94
	v_and_or_b32 v14, v15, s95, v14
	v_bfe_u32 v15, v16, 16, 1
	v_and_or_b32 v2, v2, s95, v0
	v_bfe_u32 v0, v4, 16, 1
	v_add3_u32 v15, v16, v15, s94
	v_bfe_u32 v16, v17, 16, 1
	v_add3_u32 v0, v4, v0, s94
	v_bfe_u32 v3, v5, 16, 1
	v_lshrrev_b32_e32 v15, 16, v15
	v_add3_u32 v16, v17, v16, s94
	v_lshrrev_b32_e32 v0, 16, v0
	v_add3_u32 v3, v5, v3, s94
	v_and_or_b32 v15, v16, s95, v15
	v_and_or_b32 v3, v3, s95, v0
	global_store_dwordx2 v155, v[14:15], s[6:7] offset:3072
	global_store_dwordx2 v155, v[2:3], s[6:7] offset:3584
	s_add_u32 s6, s6, 0x1000
	s_addc_u32 s7, s7, 0
	s_cmp_lt_i32 s0, s2
	s_waitcnt vmcnt(8)
	v_mov_b32_e32 v94, v86
	v_mov_b32_e32 v95, v87
	v_mov_b32_e32 v96, v88
	v_mov_b32_e32 v97, v89
	v_mov_b32_e32 v82, v74
	v_mov_b32_e32 v83, v75
	v_mov_b32_e32 v84, v76
	v_mov_b32_e32 v85, v77
	v_mov_b32_e32 v46, v66
	v_mov_b32_e32 v47, v67
	v_mov_b32_e32 v48, v68
	v_mov_b32_e32 v49, v69
	v_mov_b32_e32 v34, v58
	v_mov_b32_e32 v35, v59
	v_mov_b32_e32 v36, v60
	v_mov_b32_e32 v37, v61
	v_mov_b32_e32 v30, v70
	v_mov_b32_e32 v31, v71
	v_mov_b32_e32 v32, v72
	v_mov_b32_e32 v33, v73
	v_mov_b32_e32 v18, v62
	v_mov_b32_e32 v19, v63
	v_mov_b32_e32 v20, v64
	v_mov_b32_e32 v21, v65
	v_mov_b32_e32 v14, v54
	v_mov_b32_e32 v15, v55
	v_mov_b32_e32 v16, v56
	v_mov_b32_e32 v17, v57
	v_mov_b32_e32 v2, v50
	v_mov_b32_e32 v3, v51
	v_mov_b32_e32 v4, v52
	v_mov_b32_e32 v5, v53
	s_cbranch_scc0 .LBB0_421

; #define GAS __attribute__((address_space(1)))
; __device__ __forceinline__ unsigned pk2(float lo, float hi) { return f2bf(lo) | (f2bf(hi) << 16); }
; __device__ __forceinline__ void modulate_phase(Frame& F, const float* x, bf16* H, const float* gnorm, const float* modsub) {
;     ...
;         float s = 0.f;
; #pragma unroll
;         for (int j = 0; j < 8; ++j) s += (v[j].x * v[j].x + v[j].y * v[j].y) + (v[j].z * v[j].z + v[j].w * v[j].w);
;         const float rstd = 1.0f / sqrtf(wave_sum(s) * (1.0f / D) + RMS_EPS);
;         GAS unsigned long long* o8 = (GAS unsigned long long*)(H + (size_t)r * D) + F.lane;
; #pragma unroll
;         for (int j = 0; j < 8; ++j) { const f32x4 y = v[j] * rstd * gs[j] + sh[j];
;             o8[64 * j] = (unsigned long long)pk2(y.x, y.y) | ((unsigned long long)pk2(y.z, y.w) << 32); }
.LBB0_1734:
	s_nop 0
	v_mul_f32_e32 v0, v95, v95
	v_mul_f32_e32 v155, v97, v97
	v_fmac_f32_e32 v0, v94, v94
	v_fmac_f32_e32 v155, v96, v96
	v_add_f32_e32 v0, v0, v155
	s_nop 0
	v_mul_f32_e32 v155, v83, v83
	v_mul_f32_e32 v156, v85, v85
	v_fmac_f32_e32 v155, v82, v82
	v_fmac_f32_e32 v156, v84, v84
	v_add_f32_e32 v155, v155, v156
	v_add_f32_e32 v0, v0, v155
	s_nop 0
	v_mul_f32_e32 v155, v47, v47
	v_mul_f32_e32 v156, v49, v49
	v_fmac_f32_e32 v155, v46, v46
	v_fmac_f32_e32 v156, v48, v48
	v_add_f32_e32 v155, v155, v156
	v_add_f32_e32 v0, v155, v0
	s_nop 0
	v_mul_f32_e32 v155, v35, v35
	v_mul_f32_e32 v156, v37, v37
	v_fmac_f32_e32 v155, v34, v34
	v_fmac_f32_e32 v156, v36, v36
	v_add_f32_e32 v155, v155, v156
	v_add_f32_e32 v0, v155, v0
	s_nop 0
	v_mul_f32_e32 v155, v31, v31
	v_mul_f32_e32 v156, v33, v33
	v_fmac_f32_e32 v155, v30, v30
	v_fmac_f32_e32 v156, v32, v32
	v_add_f32_e32 v155, v155, v156
	v_add_f32_e32 v0, v155, v0
	s_nop 0
	v_mul_f32_e32 v155, v19, v19
	v_mul_f32_e32 v156, v21, v21
	v_fmac_f32_e32 v155, v18, v18
	v_fmac_f32_e32 v156, v20, v20
	v_add_f32_e32 v155, v155, v156
	v_add_f32_e32 v0, v155, v0
	s_nop 0
	v_mul_f32_e32 v155, v15, v15
	v_mul_f32_e32 v156, v17, v17
	v_fmac_f32_e32 v155, v14, v14
	v_fmac_f32_e32 v156, v16, v16
	v_add_f32_e32 v155, v155, v156
	v_add_f32_e32 v0, v155, v0
	s_nop 0
	v_mul_f32_e32 v155, v3, v3
	v_mul_f32_e32 v156, v5, v5
	v_fmac_f32_e32 v155, v2, v2
	v_fmac_f32_e32 v156, v4, v4
	v_add_f32_e32 v155, v155, v156
	v_add_f32_e32 v0, v155, v0
	ds_swizzle_b32 v155, v0 offset:swizzle(SWAP,1)
	s_waitcnt lgkmcnt(0)
	v_add_f32_e32 v0, v0, v155
	ds_swizzle_b32 v155, v0 offset:swizzle(SWAP,2)
	s_waitcnt lgkmcnt(0)
	v_add_f32_e32 v0, v0, v155
	ds_swizzle_b32 v155, v0 offset:swizzle(SWAP,4)
	s_waitcnt lgkmcnt(0)
	v_add_f32_e32 v0, v0, v155
	ds_swizzle_b32 v155, v0 offset:swizzle(SWAP,8)
	s_waitcnt lgkmcnt(0)
	v_add_f32_e32 v0, v0, v155
	ds_swizzle_b32 v155, v0 offset:swizzle(SWAP,16)
	s_waitcnt lgkmcnt(0)
	v_add_f32_e32 v0, v0, v155
	v_mov_b32_e32 v155, v0
	s_nop 1
	v_permlane32_swap_b32_e32 v0, v155
	v_add_f32_e32 v0, v0, v155
	v_fmamk_f32 v0, v0, 0x3a000000, v202
	v_mul_f32_e32 v155, 0x4f800000, v0
	v_cmp_gt_f32_e32 vcc, s60, v0
	s_nop 1
	v_cndmask_b32_e32 v0, v0, v155, vcc
	v_sqrt_f32_e32 v155, v0
	s_nop 0
	v_add_u32_e32 v156, -1, v155
	v_fma_f32 v157, -v156, v155, v0
	v_cmp_ge_f32_e64 s[40:41], 0, v157
	v_add_u32_e32 v157, 1, v155
	s_nop 0
	v_cndmask_b32_e64 v156, v155, v156, s[40:41]
	v_fma_f32 v155, -v157, v155, v0
	v_cmp_lt_f32_e64 s[40:41], 0, v155
	s_nop 1
	v_cndmask_b32_e64 v155, v156, v157, s[40:41]
	v_mul_f32_e32 v156, 0x37800000, v155
	v_cndmask_b32_e32 v155, v155, v156, vcc
	v_cmp_class_f32_e32 vcc, v0, v203
	s_nop 1
	v_cndmask_b32_e32 v0, v155, v0, vcc
	v_div_scale_f32 v155, s[10:11], v0, v0, 1.0
	v_rcp_f32_e32 v156, v155
	s_nop 0
	v_fma_f32 v157, -v155, v156, 1.0
	v_fmac_f32_e32 v156, v157, v156
	v_div_scale_f32 v157, vcc, 1.0, v0, 1.0
	v_mul_f32_e32 v158, v157, v156
	v_fma_f32 v159, -v155, v158, v157
	v_fmac_f32_e32 v158, v159, v156
	v_fma_f32 v155, -v155, v158, v157
	v_div_fmas_f32 v155, v155, v156, v158
	v_div_fixup_f32 v0, v155, v0, 1.0
	v_pk_mul_f32 v[94:95], v[94:95], v[0:1] op_sel_hi:[1,0]
	v_pk_mul_f32 v[96:97], v[96:97], v[0:1] op_sel_hi:[1,0]
	v_pk_fma_f32 v[94:95], v[6:7], v[94:95], v[10:11]
	v_pk_fma_f32 v[96:97], v[8:9], v[96:97], v[12:13]
	v_bfe_u32 v156, v94, 16, 1
	v_add3_u32 v94, v94, v156, s94
	v_bfe_u32 v156, v95, 16, 1
	v_lshrrev_b32_e32 v94, 16, v94
	v_add3_u32 v95, v95, v156, s94
	v_and_or_b32 v94, v95, s95, v94
	v_bfe_u32 v95, v96, 16, 1
	v_add3_u32 v95, v96, v95, s94
	v_bfe_u32 v96, v97, 16, 1
	v_lshrrev_b32_e32 v95, 16, v95
	v_add3_u32 v96, v97, v96, s94
	v_pk_mul_f32 v[82:83], v[82:83], v[0:1] op_sel_hi:[1,0]
	v_lshlrev_b32_e32 v155, 3, v130
	v_and_or_b32 v95, v96, s95, v95
	v_pk_fma_f32 v[82:83], v[26:27], v[82:83], v[22:23]
	global_store_dwordx2 v155, v[94:95], s[6:7]
	v_bfe_u32 v94, v82, 16, 1
	v_pk_mul_f32 v[84:85], v[84:85], v[0:1] op_sel_hi:[1,0]
	v_add3_u32 v82, v82, v94, s94
	v_bfe_u32 v94, v83, 16, 1
	v_pk_fma_f32 v[84:85], v[28:29], v[84:85], v[24:25]
	v_lshrrev_b32_e32 v82, 16, v82
	v_add3_u32 v83, v83, v94, s94
	v_and_or_b32 v82, v83, s95, v82
	v_bfe_u32 v83, v84, 16, 1
	v_add3_u32 v83, v84, v83, s94
	v_bfe_u32 v84, v85, 16, 1
	v_lshrrev_b32_e32 v83, 16, v83
	v_add3_u32 v84, v85, v84, s94
	v_pk_mul_f32 v[46:47], v[46:47], v[0:1] op_sel_hi:[1,0]
	v_and_or_b32 v83, v84, s95, v83
	v_pk_fma_f32 v[46:47], v[42:43], v[46:47], v[38:39]
	global_store_dwordx2 v155, v[82:83], s[6:7] offset:512
	v_bfe_u32 v82, v46, 16, 1
	v_pk_mul_f32 v[48:49], v[48:49], v[0:1] op_sel_hi:[1,0]
	v_add3_u32 v46, v46, v82, s94
	v_bfe_u32 v82, v47, 16, 1
	v_pk_fma_f32 v[48:49], v[44:45], v[48:49], v[40:41]
	v_lshrrev_b32_e32 v46, 16, v46
	v_add3_u32 v47, v47, v82, s94
	v_and_or_b32 v46, v47, s95, v46
	v_bfe_u32 v47, v48, 16, 1
	v_add3_u32 v47, v48, v47, s94
	v_bfe_u32 v48, v49, 16, 1
	v_lshrrev_b32_e32 v47, 16, v47
	v_add3_u32 v48, v49, v48, s94
	v_pk_mul_f32 v[34:35], v[34:35], v[0:1] op_sel_hi:[1,0]
	v_and_or_b32 v47, v48, s95, v47
	v_pk_fma_f32 v[34:35], v[90:91], v[34:35], v[78:79]
	global_store_dwordx2 v155, v[46:47], s[6:7] offset:1024
	v_bfe_u32 v46, v34, 16, 1
	v_pk_mul_f32 v[36:37], v[36:37], v[0:1] op_sel_hi:[1,0]
	v_add3_u32 v34, v34, v46, s94
	v_bfe_u32 v46, v35, 16, 1
	v_pk_fma_f32 v[36:37], v[92:93], v[36:37], v[80:81]
	v_lshrrev_b32_e32 v34, 16, v34
	v_add3_u32 v35, v35, v46, s94
	v_and_or_b32 v34, v35, s95, v34
	v_bfe_u32 v35, v36, 16, 1
	v_add3_u32 v35, v36, v35, s94
	v_bfe_u32 v36, v37, 16, 1
	v_lshrrev_b32_e32 v35, 16, v35
	v_add3_u32 v36, v37, v36, s94
; #define GAS __attribute__((address_space(1)))
; __device__ __forceinline__ unsigned pk2(float lo, float hi) { return f2bf(lo) | (f2bf(hi) << 16); }
; __device__ __forceinline__ void modulate_phase(Frame& F, const float* x, bf16* H, const float* gnorm, const float* modsub) {
;     ...
;         GAS unsigned long long* o8 = (GAS unsigned long long*)(H + (size_t)r * D) + F.lane;
; #pragma unroll
;         for (int j = 0; j < 8; ++j) { const f32x4 y = v[j] * rstd * gs[j] + sh[j];
;             o8[64 * j] = (unsigned long long)pk2(y.x, y.y) | ((unsigned long long)pk2(y.z, y.w) << 32); }
; #pragma unroll
;         for (int j = 0; j < 8; ++j) v[j] = nv[j];
	v_pk_mul_f32 v[30:31], v[30:31], v[0:1] op_sel_hi:[1,0]
	v_and_or_b32 v35, v36, s95, v35
	v_pk_fma_f32 v[30:31], v[102:103], v[30:31], v[98:99]
	global_store_dwordx2 v155, v[34:35], s[6:7] offset:1536
	v_bfe_u32 v34, v30, 16, 1
	v_pk_mul_f32 v[32:33], v[32:33], v[0:1] op_sel_hi:[1,0]
	v_add3_u32 v30, v30, v34, s94
	v_bfe_u32 v34, v31, 16, 1
	v_pk_fma_f32 v[32:33], v[104:105], v[32:33], v[100:101]
	v_lshrrev_b32_e32 v30, 16, v30
	v_add3_u32 v31, v31, v34, s94
	v_and_or_b32 v30, v31, s95, v30
	v_bfe_u32 v31, v32, 16, 1
	v_add3_u32 v31, v32, v31, s94
	v_bfe_u32 v32, v33, 16, 1
	v_lshrrev_b32_e32 v31, 16, v31
	v_add3_u32 v32, v33, v32, s94
	v_pk_mul_f32 v[18:19], v[18:19], v[0:1] op_sel_hi:[1,0]
	v_and_or_b32 v31, v32, s95, v31
	v_pk_fma_f32 v[18:19], v[110:111], v[18:19], v[106:107]
	global_store_dwordx2 v155, v[30:31], s[6:7] offset:2048
	v_bfe_u32 v30, v18, 16, 1
	v_pk_mul_f32 v[20:21], v[20:21], v[0:1] op_sel_hi:[1,0]
	v_add3_u32 v18, v18, v30, s94
	v_bfe_u32 v30, v19, 16, 1
	v_pk_fma_f32 v[20:21], v[112:113], v[20:21], v[108:109]
	v_lshrrev_b32_e32 v18, 16, v18
	v_add3_u32 v19, v19, v30, s94
	v_and_or_b32 v18, v19, s95, v18
	v_bfe_u32 v19, v20, 16, 1
	v_add3_u32 v19, v20, v19, s94
	v_bfe_u32 v20, v21, 16, 1
	v_lshrrev_b32_e32 v19, 16, v19
	v_add3_u32 v20, v21, v20, s94
	v_pk_mul_f32 v[14:15], v[14:15], v[0:1] op_sel_hi:[1,0]
	v_pk_mul_f32 v[2:3], v[2:3], v[0:1] op_sel_hi:[1,0]
	v_and_or_b32 v19, v20, s95, v19
	v_pk_fma_f32 v[14:15], v[118:119], v[14:15], v[114:115]
	s_waitcnt vmcnt(5)
	v_pk_fma_f32 v[2:3], v[122:123], v[2:3], v[126:127]
	global_store_dwordx2 v155, v[18:19], s[6:7] offset:2560
	v_pk_mul_f32 v[16:17], v[16:17], v[0:1] op_sel_hi:[1,0]
	v_bfe_u32 v18, v14, 16, 1
	v_pk_mul_f32 v[4:5], v[4:5], v[0:1] op_sel_hi:[1,0]
	v_bfe_u32 v0, v2, 16, 1
	v_add3_u32 v14, v14, v18, s94
	v_bfe_u32 v18, v15, 16, 1
	v_add3_u32 v0, v2, v0, s94
	v_bfe_u32 v2, v3, 16, 1
	v_pk_fma_f32 v[16:17], v[120:121], v[16:17], v[116:117]
	v_lshrrev_b32_e32 v14, 16, v14
	v_add3_u32 v15, v15, v18, s94
	v_pk_fma_f32 v[4:5], v[124:125], v[4:5], v[128:129]
	v_lshrrev_b32_e32 v0, 16, v0
	v_add3_u32 v2, v3, v2, s94
	v_and_or_b32 v14, v15, s95, v14
	v_bfe_u32 v15, v16, 16, 1
	v_and_or_b32 v2, v2, s95, v0
	v_bfe_u32 v0, v4, 16, 1
	v_add3_u32 v15, v16, v15, s94
	v_bfe_u32 v16, v17, 16, 1
	v_add3_u32 v0, v4, v0, s94
	v_bfe_u32 v3, v5, 16, 1
	v_lshrrev_b32_e32 v15, 16, v15
	v_add3_u32 v16, v17, v16, s94
	v_lshrrev_b32_e32 v0, 16, v0
	v_add3_u32 v3, v5, v3, s94
	v_and_or_b32 v15, v16, s95, v15
	v_and_or_b32 v3, v3, s95, v0
	global_store_dwordx2 v155, v[14:15], s[6:7] offset:3072
	global_store_dwordx2 v155, v[2:3], s[6:7] offset:3584
	s_add_u32 s6, s6, 0x1000
	s_addc_u32 s7, s7, 0
	s_cmp_lt_i32 s0, s2
	v_mov_b32_e32 v94, v86
	v_mov_b32_e32 v95, v87
	v_mov_b32_e32 v96, v88
	v_mov_b32_e32 v97, v89
	v_mov_b32_e32 v82, v74
	v_mov_b32_e32 v83, v75
	v_mov_b32_e32 v84, v76
	v_mov_b32_e32 v85, v77
	v_mov_b32_e32 v46, v66
	v_mov_b32_e32 v47, v67
	v_mov_b32_e32 v48, v68
	v_mov_b32_e32 v49, v69
	v_mov_b32_e32 v34, v58
	v_mov_b32_e32 v35, v59
	v_mov_b32_e32 v36, v60
	v_mov_b32_e32 v37, v61
	v_mov_b32_e32 v30, v70
	v_mov_b32_e32 v31, v71
	v_mov_b32_e32 v32, v72
	v_mov_b32_e32 v33, v73
	v_mov_b32_e32 v18, v62
	v_mov_b32_e32 v19, v63
	v_mov_b32_e32 v20, v64
	v_mov_b32_e32 v21, v65
	v_mov_b32_e32 v14, v54
	v_mov_b32_e32 v15, v55
	v_mov_b32_e32 v16, v56
	v_mov_b32_e32 v17, v57
	v_mov_b32_e32 v2, v50
	v_mov_b32_e32 v3, v51
	v_mov_b32_e32 v4, v52
	v_mov_b32_e32 v5, v53
	s_cbranch_scc0 .LBB0_1737
; __device__ __forceinline__ int fresh_lane() { unsigned z = 0u; asm volatile("" : "+v"(z)); return (int)__builtin_amdgcn_mbcnt_hi(~0u, __builtin_amdgcn_mbcnt_lo(~0u, z)); }
; #define GAS __attribute__((address_space(1)))
; __device__ __forceinline__ void xcd_barrier(const XcdBarrier& b, int wave_s) {
;     asm volatile("s_waitcnt vmcnt(0)" ::: "memory");
;     __syncthreads();
;     if (wave_s == 0 && fresh_lane() == 0) {
;         unsigned* bar = b.bar; asm volatile("" : "+s"(bar));
;         __builtin_amdgcn_s_waitcnt(0);
;         unsigned nloc = b.st[0], nx = b.st[1];
;         if (nloc == 0u) { xcd_barrier_complete(bar, b.x, nloc, nx); b.st[0] = nloc; b.st[1] = nx; }
; __device__ __forceinline__ void modulate_phase(Frame& F, const float* x, bf16* H, const float* gnorm, const float* modsub) {
;     ...
;     for (int r = rbeg; r < rend; ++r) {
;         { const GAS f32x4* xn = (const GAS f32x4*)(x + (size_t)min(r + 1, rend - 1) * D) + F.lane;
; #pragma unroll
;           for (int j = 0; j < 8; ++j) nv[j] = xn[64 * j]; }
;         const int b = r >> 12;
;         if (b != curb) { curb = b;
; #pragma unroll
;             for (int j = 0; j < 8; ++j) { const int c = 4 * F.lane + 256 * j;
;                 const f32x4 g = *(const GAS f32x4*)(gnorm + c), sc = *(const GAS f32x4*)(modsub + (size_t)b * NMOD + D + c);
;                 gs[j] = g * (sc + 1.0f); sh[j] = *(const GAS f32x4*)(modsub + (size_t)b * NMOD + c); } }
.LBB0_1735:
	s_mov_b32 s1, s0
	s_add_i32 s0, s0, 1
	s_min_i32 s10, s0, s16
	s_ashr_i32 s11, s10, 31
	s_lshl_b64 s[10:11], s[10:11], 13
	s_add_u32 s10, s12, s10
	s_addc_u32 s11, s13, s11
	v_lshlrev_b32_e32 v0, 4, v130
	v_lshl_add_u64 v[50:51], s[10:11], 0, v[0:1]
	v_add_co_u32_e32 v50, vcc, 0x1000, v50
	global_load_dwordx4 v[86:89], v0, s[10:11]
	global_load_dwordx4 v[74:77], v0, s[10:11] offset:1024
	global_load_dwordx4 v[66:69], v0, s[10:11] offset:2048
	global_load_dwordx4 v[58:61], v0, s[10:11] offset:3072
	v_addc_co_u32_e32 v51, vcc, 0, v51, vcc
	global_load_dwordx4 v[70:73], v[50:51], off
	global_load_dwordx4 v[62:65], v[50:51], off offset:1024
	global_load_dwordx4 v[54:57], v[50:51], off offset:2048
	s_nop 0
	global_load_dwordx4 v[50:53], v[50:51], off offset:3072
	s_ashr_i32 s1, s1, 12
	s_cmp_eq_u32 s1, s8
	s_cbranch_scc1 .LBB0_1734
	s_mul_i32 s8, s1, 0x12000
	s_mul_hi_i32 s9, s1, 0x12000
	s_add_u32 s8, s14, s8
	s_addc_u32 s9, s15, s9
	s_add_u32 s10, s8, 0x2000
	s_addc_u32 s11, s9, 0
	global_load_dwordx4 v[6:9], v[132:133], off
	global_load_dwordx4 v[10:13], v131, s[10:11]
	s_waitcnt vmcnt(0)
	v_pk_add_f32 v[12:13], v[12:13], 1.0 op_sel_hi:[1,0]
	v_pk_add_f32 v[10:11], v[10:11], 1.0 op_sel_hi:[1,0]
	v_pk_mul_f32 v[8:9], v[8:9], v[12:13]
	v_pk_mul_f32 v[6:7], v[6:7], v[10:11]
	global_load_dwordx4 v[10:13], v131, s[8:9]
	global_load_dwordx4 v[22:25], v[134:135], off
	global_load_dwordx4 v[26:29], v148, s[10:11]
	s_waitcnt vmcnt(0)
	v_pk_add_f32 v[28:29], v[28:29], 1.0 op_sel_hi:[1,0]
	v_pk_add_f32 v[26:27], v[26:27], 1.0 op_sel_hi:[1,0]
	v_pk_mul_f32 v[28:29], v[24:25], v[28:29]
	v_pk_mul_f32 v[26:27], v[22:23], v[26:27]
	global_load_dwordx4 v[22:25], v131, s[8:9] offset:1024
	global_load_dwordx4 v[38:41], v[136:137], off
	global_load_dwordx4 v[42:45], v149, s[10:11]
	s_waitcnt vmcnt(0)
	v_pk_add_f32 v[44:45], v[44:45], 1.0 op_sel_hi:[1,0]
	v_pk_add_f32 v[42:43], v[42:43], 1.0 op_sel_hi:[1,0]
	v_pk_mul_f32 v[44:45], v[40:41], v[44:45]
	v_pk_mul_f32 v[42:43], v[38:39], v[42:43]
	global_load_dwordx4 v[38:41], v131, s[8:9] offset:2048
	global_load_dwordx4 v[78:81], v[138:139], off
	global_load_dwordx4 v[90:93], v150, s[10:11]
	s_waitcnt vmcnt(0)
	v_pk_add_f32 v[92:93], v[92:93], 1.0 op_sel_hi:[1,0]
	v_pk_add_f32 v[90:91], v[90:91], 1.0 op_sel_hi:[1,0]
	v_pk_mul_f32 v[92:93], v[80:81], v[92:93]
	v_pk_mul_f32 v[90:91], v[78:79], v[90:91]
	global_load_dwordx4 v[78:81], v131, s[8:9] offset:3072
	global_load_dwordx4 v[98:101], v[140:141], off
	global_load_dwordx4 v[102:105], v151, s[10:11]
	s_waitcnt vmcnt(0)
	v_pk_add_f32 v[104:105], v[104:105], 1.0 op_sel_hi:[1,0]
	v_pk_add_f32 v[102:103], v[102:103], 1.0 op_sel_hi:[1,0]
	v_pk_mul_f32 v[104:105], v[100:101], v[104:105]
	v_pk_mul_f32 v[102:103], v[98:99], v[102:103]
	global_load_dwordx4 v[98:101], v151, s[8:9]
	global_load_dwordx4 v[106:109], v[142:143], off
	global_load_dwordx4 v[110:113], v152, s[10:11]
	s_waitcnt vmcnt(0)
	v_pk_add_f32 v[112:113], v[112:113], 1.0 op_sel_hi:[1,0]
	v_pk_add_f32 v[110:111], v[110:111], 1.0 op_sel_hi:[1,0]
	v_pk_mul_f32 v[112:113], v[108:109], v[112:113]
	v_pk_mul_f32 v[110:111], v[106:107], v[110:111]
	global_load_dwordx4 v[106:109], v152, s[8:9]
	global_load_dwordx4 v[114:117], v[144:145], off
	global_load_dwordx4 v[118:121], v153, s[10:11]
	s_waitcnt vmcnt(0)
	v_pk_add_f32 v[120:121], v[120:121], 1.0 op_sel_hi:[1,0]
	v_pk_add_f32 v[118:119], v[118:119], 1.0 op_sel_hi:[1,0]
	v_pk_mul_f32 v[120:121], v[116:117], v[120:121]
	v_pk_mul_f32 v[118:119], v[114:115], v[118:119]
	global_load_dwordx4 v[114:117], v153, s[8:9]
	global_load_dwordx4 v[122:125], v[146:147], off
	global_load_dwordx4 v[126:129], v154, s[10:11]
	s_waitcnt vmcnt(0)
	v_pk_add_f32 v[128:129], v[128:129], 1.0 op_sel_hi:[1,0]
	v_pk_add_f32 v[126:127], v[126:127], 1.0 op_sel_hi:[1,0]
	v_pk_mul_f32 v[124:125], v[124:125], v[128:129]
	v_pk_mul_f32 v[122:123], v[122:123], v[126:127]
	global_load_dwordx4 v[126:129], v154, s[8:9]
	s_waitcnt vmcnt(0)
	s_mov_b32 s8, s1
	s_branch .LBB0_1734
.LBB0_1737:
	v_readlane_b32 s0, v253, 14
	s_add_i32 s2, s0, 13
	s_cmp_ge_i32 s2, s91
	s_cbranch_scc1 .LBB0_1785
	s_waitcnt vmcnt(0)
	v_readlane_b32 s0, v253, 29
	v_readlane_b32 s1, v253, 30
	s_andn2_b64 vcc, exec, s[0:1]
	s_waitcnt vmcnt(0)
	s_barrier
	s_cbranch_vccnz .LBB0_1784
	v_mov_b32_e32 v0, v1
	s_nop 0
	v_mbcnt_lo_u32_b32 v0, -1, v0
	v_mbcnt_hi_u32_b32 v0, -1, v0
	v_cmp_eq_u32_e32 vcc, 0, v0
	s_and_saveexec_b64 s[0:1], vcc
	s_cbranch_execz .LBB0_1783
	v_readlane_b32 s6, v253, 4
	v_readlane_b32 s8, v255, 37
	v_readlane_b32 s7, v253, 5
	s_waitcnt vmcnt(0) expcnt(0) lgkmcnt(0)
	v_mov_b32_e32 v0, s8
	ds_read_b32 v2, v0
	v_readlane_b32 s8, v255, 38
	s_waitcnt lgkmcnt(0)
	v_cmp_ne_u32_e32 vcc, 0, v2
	v_mov_b32_e32 v0, s8
	ds_read_b32 v0, v0
	s_cbranch_vccnz .LBB0_1754
	v_readlane_b32 s8, v253, 0
	v_readlane_b32 s9, v253, 1
	s_load_dwordx2 s[12:13], s[8:9], 0x4
	s_add_u32 s8, s6, 0x1000
	s_addc_u32 s9, s7, 0
	s_add_u32 s10, s6, 0x1100
	s_addc_u32 s11, s7, 0
	s_waitcnt lgkmcnt(0)
	s_mul_i32 s22, s12, s86
	s_add_u32 s12, s6, 0x1200
	s_mul_i32 s22, s22, s13
	s_addc_u32 s13, s7, 0
	s_add_u32 s14, s6, 0x1300
	s_addc_u32 s15, s7, 0
	s_mov_b32 s26, 1
	s_mov_b64 s[16:17], 0
	s_branch .LBB0_1744
